# READY flags kept L2-resident (plain stores) when all quarter-workgroups share an XCD (census guard)
# speedup vs baseline: 1.0257x; 1.0190x over previous
; #define LAS __attribute__((address_space(3)))
; #define MFMA32(a, b, c) __builtin_amdgcn_mfma_f32_16x16x32_bf16(a, b, c, 0, 0, 0)
; #define RD_PREFETCH_A(cc) do { const int soA_ = (b * SEQ + 16 * (cc)) * 256; \
;                 _Pragma("unroll") for (int ks = 0; ks < 3; ++ks) { nAW[ks] = __builtin_bit_cast(bf16x8, __builtin_amdgcn_raw_buffer_load_b128(rsWS, voA + 64 * ks, (int)WS_AW + soA_, 0)); nAA[ks] = __builtin_bit_cast(bf16x8, __builtin_amdgcn_raw_buffer_load_b128(rsWS, voA + 64 * ks, (int)WS_AA + soA_, 0)); } } while (0)
; __device__ void phase_rwkv_dist(const Params& p, LAS unsigned char* lds, int wg, int nwg) {
;     ...
;             for (int cj = 0; cj < 2 * ((RC_NCHK + 23) / 24); ++cj) {
;                 const int ci = 24 * (cj >> 1) + 6 * qw + pw + 3 * (cj & 1); if (ci >= RC_NCHK) continue;
;                 const int cn = 24 * ((cj + 1) >> 1) + 6 * qw + pw + 3 * ((cj + 1) & 1);
;                 RD_PREFETCH_R(ci);
;                 const size_t m = (size_t)b * SEQ + 16 * ci + r; const bool first = (16 * ci + r) == 0;
;                 f32x4 accw[4], acca[4];
; #pragma unroll
;                 for (int nt = 0; nt < 4; ++nt) { accw[nt] = zero4; acca[nt] = zero4; }
; #pragma unroll
;                 for (int ks = 0; ks < 3; ++ks)
; #pragma unroll
;                     for (int nt = 0; nt < 4; ++nt) { const int bo = (16 * nt * 104 + 32 * ks) * 2;
;                         accw[nt] = MFMA32(*(LAS const bf16x8*)(wb + bo), nAW[ks], accw[nt]); acca[nt] = MFMA32(*(LAS const bf16x8*)(wb + 13312 + bo), nAA[ks], acca[nt]); }
;                 __builtin_amdgcn_sched_barrier(0);
;                 if (cn < RC_NCHK) RD_PREFETCH_A(cn);
;     ...
;                 __hip_atomic_store(READY + bh * 512 + ci, 1u, __ATOMIC_RELAXED, __HIP_MEMORY_SCOPE_AGENT);
.LBB0_653:
	s_lshr_b32 s2, s43, 1
	s_mul_i32 s2, s2, 24
	s_bitcmp1_b32 s43, 0
	s_cselect_b32 s3, 3, 0
	s_add_i32 s2, s2, s16
	s_add_i32 s62, s2, s3
	s_add_i32 s43, s43, 1
	s_cmpk_gt_i32 s62, 0x1ff
	s_cbranch_scc1 .LBB0_652
	ds_read_b128 v[52:55], v138
	ds_read_b128 v[56:59], v138 offset:64
	ds_read_b128 v[60:63], v138 offset:13312
	ds_read_b128 v[64:67], v138 offset:13376
	ds_read_b128 v[68:71], v138 offset:3328
	ds_read_b128 v[72:75], v138 offset:128
	ds_read_b128 v[76:79], v138 offset:16640
	ds_read_b128 v[80:83], v138 offset:13440
	s_waitcnt vmcnt(5) lgkmcnt(7)
	v_mfma_f32_16x16x32_bf16 v[52:55], v[52:55], v[28:31], 0
	ds_read_b128 v[84:87], v138 offset:6656
	ds_read_b128 v[88:91], v138 offset:6720
	ds_read_b128 v[92:95], v138 offset:19968
	ds_read_b128 v[96:99], v138 offset:20032
	ds_read_b128 v[100:103], v138 offset:9984
	ds_read_b128 v[104:107], v138 offset:6784
	s_waitcnt vmcnt(4) lgkmcnt(11)
	v_mfma_f32_16x16x32_bf16 v[60:63], v[60:63], v[40:43], 0
	ds_read_b128 v[108:111], v138 offset:23296
	ds_read_b128 v[116:119], v138 offset:20096
	s_lshr_b32 s2, s43, 1
	s_mul_i32 s2, s2, 24
	s_waitcnt lgkmcnt(11)
	v_mfma_f32_16x16x32_bf16 v[68:71], v[68:71], v[28:31], 0
	s_bitcmp1_b32 s43, 0
	s_cselect_b32 s3, 3, 0
	s_add_i32 s2, s2, s16
	s_waitcnt vmcnt(3)
	v_mfma_f32_16x16x32_bf16 v[52:55], v[56:59], v[32:35], v[52:55]
	s_add_i32 s2, s2, s3
	s_lshl_b32 s3, s62, 11
	s_add_i32 s3, s3, s18
	s_waitcnt vmcnt(2)
	v_mfma_f32_16x16x32_bf16 v[56:59], v[64:67], v[44:47], v[60:63]
	s_nop 2
	ds_read_b128 v[60:63], v138 offset:3392
	ds_read_b128 v[64:67], v138 offset:3456
	s_add_i32 s6, s3, 0xffffff80
	s_cmp_gt_i32 s3, 0
	s_waitcnt lgkmcnt(11)
	v_mfma_f32_16x16x32_bf16 v[76:79], v[76:79], v[40:43], 0
	s_cselect_b32 s6, s6, 0
	s_cselect_b32 s7, 0, 0xffffff80
	s_add_i32 s38, s3, 0x13800000
	s_waitcnt lgkmcnt(9)
	v_mfma_f32_16x16x32_bf16 v[84:87], v[84:87], v[28:31], 0
	v_add_u32_e32 v0, s7, v191
	s_add_i32 s39, s6, 0x13800000
	s_add_i32 s3, s3, 0x17800000
	s_waitcnt lgkmcnt(1)
	v_mfma_f32_16x16x32_bf16 v[60:63], v[60:63], v[32:35], v[68:71]
	s_nop 2
	ds_read_b128 v[68:71], v138 offset:16704
	ds_read_b128 v[112:115], v138 offset:16768
	ds_read_b128 v[128:131], v138 offset:10112
	ds_read_b128 v[140:143], v138 offset:23424
	s_waitcnt lgkmcnt(3)
	v_mfma_f32_16x16x32_bf16 v[68:71], v[68:71], v[44:47], v[76:79]
	s_add_i32 s6, s6, 0x17800000
	s_nop 1
	ds_read_b128 v[76:79], v138 offset:10048
	v_mfma_f32_16x16x32_bf16 v[120:123], v[88:91], v[32:35], v[84:87]
	s_nop 2
	ds_read_b128 v[84:87], v138 offset:23360
	v_mfma_f32_16x16x32_bf16 v[92:95], v[92:95], v[40:43], 0
	v_mfma_f32_16x16x32_bf16 v[100:103], v[100:103], v[28:31], 0
	v_mfma_f32_16x16x32_bf16 v[108:111], v[108:111], v[40:43], 0
	v_mfma_f32_16x16x32_bf16 v[124:127], v[96:99], v[44:47], v[92:95]
	s_waitcnt vmcnt(1)
	v_mfma_f32_16x16x32_bf16 v[52:55], v[72:75], v[36:39], v[52:55]
	v_add_u32_e32 v73, s7, v208
	v_add_u32_e32 v72, s7, v207
	v_add_u32_e32 v74, s7, v209
	s_waitcnt lgkmcnt(1)
	v_mfma_f32_16x16x32_bf16 v[132:135], v[76:79], v[32:35], v[100:103]
	s_waitcnt lgkmcnt(0)
	v_mfma_f32_16x16x32_bf16 v[144:147], v[84:87], v[44:47], v[108:111]
	s_waitcnt vmcnt(0)
	v_mfma_f32_16x16x32_bf16 v[56:59], v[80:83], v[48:51], v[56:59]
	v_mfma_f32_16x16x32_bf16 v[84:87], v[64:67], v[36:39], v[60:63]
	v_mfma_f32_16x16x32_bf16 v[88:91], v[112:115], v[48:51], v[68:71]
	v_mfma_f32_16x16x32_bf16 v[76:79], v[104:107], v[36:39], v[120:123]
	v_mfma_f32_16x16x32_bf16 v[80:83], v[116:119], v[48:51], v[124:127]
	v_mfma_f32_16x16x32_bf16 v[68:71], v[128:131], v[36:39], v[132:135]
	v_mfma_f32_16x16x32_bf16 v[72:75], v[140:143], v[48:51], v[144:147]
	s_waitcnt vmcnt(0)
	s_cmp_lt_i32 s90, 0
	s_cbranch_scc1 .Lprep_nopend
	s_lshl_b32 s86, s90, 2
	s_add_u32 s86, s41, s86
	s_addc_u32 s87, s42, 0
	s_cmp_eq_u32 s91, 0
	s_cbranch_scc1 .Lrfl0s
	global_store_dword v1, v218, s[86:87]
	s_branch .Lrfl0d
.Lrfl0s:
	global_store_dword v1, v218, s[86:87] sc1
.Lrfl0d:
	s_mov_b32 s90, -1

; __device__ void phase_rwkv_dist(const Params& p, LAS unsigned char* lds, int wg, int nwg) {
;     ...
;                 asm volatile("s_waitcnt vmcnt(0)" ::: "memory");
;                 __hip_atomic_store(READY + bh * 512 + ci, 1u, __ATOMIC_RELAXED, __HIP_MEMORY_SCOPE_AGENT);
.LBB0_668:
	s_cmp_lt_i32 s90, 0
	s_cbranch_scc1 .Lprep_noflush
	s_waitcnt vmcnt(0)
	s_lshl_b32 s86, s90, 2
	s_add_u32 s86, s41, s86
	s_addc_u32 s87, s42, 0
	s_cmp_eq_u32 s91, 0
	s_cbranch_scc1 .Lrfl1s
	global_store_dword v1, v218, s[86:87]
	s_branch .Lrfl1d
